# attention: mask-word load issued before the K/V tile prefetch loads so the mid-step wait is vmcnt(4) not vmcnt(0) (K/V prefetch stays in flight)
# speedup vs baseline: 1.0068x; 1.0068x over previous
; __device__ __forceinline__ void finishSM(f32x16& p0, f32x16& p1, float alpha, float& l_reg, bf16x8& pa0, bf16x8& pa1, bf16x8& pa2, bf16x8& pa3) {
; #pragma unroll
;     for (int r = 0; r < 16; ++r) p1[r] = __builtin_amdgcn_exp2f(p1[r]);
;     float ps = 0;
; #pragma unroll
;     for (int r = 0; r < 16; ++r) ps += p0[r];
; #pragma unroll
;     for (int r = 0; r < 16; ++r) ps += p1[r];
;     { auto rr = __builtin_amdgcn_permlane32_swap(__float_as_uint(ps), __float_as_uint(ps), false, false);
;       ps = __uint_as_float(rr[0]) + __uint_as_float(rr[1]); }
;     l_reg = l_reg * alpha + ps;
;     ...
;     PK4(p0, 0, pa0); PK4(p0, 8, pa1); PK4(p1, 0, pa2); PK4(p1, 8, pa3);
;     ...
; }
; template <int KB>
; __device__ __forceinline__ void qkt(f32x16& p0, f32x16& p1, const char* K_lds, int r32, int hi, const bf16x8* qr) {
;     p0 = f32x16{}; p1 = f32x16{};
;     const char* kb[4];
; #pragma unroll
;     for (int dd = 0; dd < 4; ++dd) kb[dd] = K_lds + KB * SHM_K + KSWZ(r32, (dd * 16 + hi * 8) * 2);
; #pragma unroll
;     for (int d0 = 0; d0 < 8; ++d0) { const char* a = kb[d0 & 3] + (d0 >> 2) * 128;
;         bf16x8 b0 = *reinterpret_cast<const bf16x8*>(a);
;         bf16x8 b1 = *reinterpret_cast<const bf16x8*>(a + 32 * 256);
;         p0 = __builtin_amdgcn_mfma_f32_32x32x16_bf16(b0, qr[d0], p0, 0, 0, 0);
;         p1 = __builtin_amdgcn_mfma_f32_32x32x16_bf16(b1, qr[d0], p1, 0, 0, 0); }
; }
.LBB0_1299:
	ds_read_b128 v[66:69], v199 offset:49152
	ds_read_b128 v[130:133], v199 offset:49280
	ds_read_b128 v[82:85], v199 offset:57344
	ds_read_b128 v[134:137], v199 offset:57472
	ds_read_b128 v[138:141], v200 offset:49152
	ds_read_b128 v[142:145], v200 offset:57344
	ds_read_b128 v[146:149], v200 offset:49280
	v_exp_f32_e32 v209, v150
	s_waitcnt lgkmcnt(6)
	v_mfma_f32_32x32x16_bf16 v[66:81], v[66:69], v[126:129], 0
	v_add_f32_e32 v150, 0, v219
	v_add_f32_e32 v150, v220, v150
	v_add_f32_e32 v150, v221, v150
	v_add_f32_e32 v150, v222, v150
	v_add_f32_e32 v150, v223, v150
	v_add_f32_e32 v150, v225, v150
	v_add_f32_e32 v150, v224, v150
	s_waitcnt lgkmcnt(4)
	v_mfma_f32_32x32x16_bf16 v[82:97], v[82:85], v[126:129], 0
	v_add_f32_e32 v150, v226, v150
	v_add_f32_e32 v150, v211, v150
	v_add_f32_e32 v150, v212, v150
	v_exp_f32_e32 v194, v194
	v_exp_f32_e32 v195, v195
	v_exp_f32_e32 v192, v192
	v_exp_f32_e32 v193, v193
	s_waitcnt lgkmcnt(2)
	v_mfma_f32_32x32x16_bf16 v[66:81], v[138:141], v[122:125], v[66:81]
	ds_read_b128 v[138:141], v200 offset:57472
	ds_read_b128 v[228:231], v201 offset:49152
	ds_read_b128 v[232:235], v201 offset:49280
	ds_read_b128 v[236:239], v201 offset:57344
	ds_read_b128 v[240:243], v201 offset:57472
	ds_read_b128 v[244:247], v202 offset:49152
	ds_read_b128 v[248:251], v202 offset:49280
	v_exp_f32_e32 v158, v158
	v_exp_f32_e32 v159, v159
	v_exp_f32_e32 v207, v154
	v_exp_f32_e32 v208, v155
	v_exp_f32_e32 v210, v151
	v_exp_f32_e32 v160, v160
	s_waitcnt lgkmcnt(8)
	v_mfma_f32_32x32x16_bf16 v[82:97], v[142:145], v[122:125], v[82:97]
	ds_read_b128 v[142:145], v202 offset:57344
	ds_read_b128 v[172:175], v202 offset:57472
	v_exp_f32_e32 v161, v161
	v_exp_f32_e32 v227, v156
	v_cvt_pk_bf16_f32 v151, v224, v226
	v_cvt_pk_bf16_f32 v154, v214, v216
	v_cvt_pk_bf16_f32 v155, v217, v218
	v_cvt_pk_bf16_f32 v156, v194, v195
	s_waitcnt lgkmcnt(7)
	v_mfma_f32_32x32x16_bf16 v[66:81], v[228:231], v[118:121], v[66:81]
	v_exp_f32_e32 v228, v157
	v_exp_f32_e32 v229, v152
	v_exp_f32_e32 v230, v153
	v_cvt_pk_bf16_f32 v152, v211, v212
	v_cvt_pk_bf16_f32 v153, v213, v215
	v_cvt_pk_bf16_f32 v157, v192, v193
	v_cvt_pk_bf16_f32 v211, v229, v230
	s_waitcnt lgkmcnt(5)
	v_mfma_f32_32x32x16_bf16 v[82:97], v[236:239], v[118:121], v[82:97]
	v_permlane32_swap_b32_e32 v152, v154
	v_permlane32_swap_b32_e32 v153, v155
	s_waitcnt lgkmcnt(3)
	v_mfma_f32_32x32x16_bf16 v[66:81], v[244:247], v[114:117], v[66:81]
	s_waitcnt lgkmcnt(1)
	v_mfma_f32_32x32x16_bf16 v[82:97], v[142:145], v[114:117], v[82:97]
	v_add_f32_e32 v142, v213, v150
	v_add_f32_e32 v142, v215, v142
	v_add_f32_e32 v142, v214, v142
	v_add_f32_e32 v142, v216, v142
	v_add_f32_e32 v142, v217, v142
	v_add_f32_e32 v142, v218, v142
	v_add_f32_e32 v142, v194, v142
	v_mfma_f32_32x32x16_bf16 v[66:81], v[130:133], v[110:113], v[66:81]
	v_add_f32_e32 v130, v195, v142
	v_add_f32_e32 v130, v192, v130
	v_add_f32_e32 v130, v193, v130
	v_add_f32_e32 v130, v158, v130
	v_add_f32_e32 v130, v159, v130
	v_add_f32_e32 v130, v207, v130
	v_add_f32_e32 v130, v208, v130
	v_mfma_f32_32x32x16_bf16 v[82:97], v[134:137], v[110:113], v[82:97]
	v_add_f32_e32 v130, v209, v130
	v_add_f32_e32 v130, v210, v130
	v_add_f32_e32 v130, v160, v130
	v_add_f32_e32 v130, v161, v130
	v_add_f32_e32 v130, v227, v130
	v_add_f32_e32 v130, v228, v130
	v_add_f32_e32 v130, v229, v130
	v_mfma_f32_32x32x16_bf16 v[66:81], v[146:149], v[106:109], v[66:81]
	v_add_f32_e32 v181, v230, v130
	v_mov_b32_e32 v187, v181
	v_cvt_pk_bf16_f32 v148, v219, v220
	v_cvt_pk_bf16_f32 v149, v221, v222
	v_cvt_pk_bf16_f32 v150, v223, v225
	v_cvt_pk_bf16_f32 v158, v158, v159
	v_cvt_pk_bf16_f32 v159, v207, v208
	v_mfma_f32_32x32x16_bf16 v[82:97], v[138:141], v[106:109], v[82:97]
	v_cvt_pk_bf16_f32 v208, v209, v210
	v_cvt_pk_bf16_f32 v210, v227, v228
	v_permlane32_swap_b32_e32 v181, v187
	v_permlane32_swap_b32_e32 v148, v150
	v_permlane32_swap_b32_e32 v149, v151
	v_mfma_f32_32x32x16_bf16 v[66:81], v[232:235], v[102:105], v[66:81]
	v_cvt_pk_bf16_f32 v209, v160, v161
	v_permlane32_swap_b32_e32 v208, v210
	v_permlane32_swap_b32_e32 v156, v158
	v_permlane32_swap_b32_e32 v157, v159
	v_mfma_f32_32x32x16_bf16 v[82:97], v[240:243], v[102:105], v[82:97]
	v_permlane32_swap_b32_e32 v209, v211
	v_mfma_f32_32x32x16_bf16 v[66:81], v[248:251], v[98:101], v[66:81]
	s_waitcnt lgkmcnt(0)
	v_mfma_f32_32x32x16_bf16 v[82:97], v[172:175], v[98:101], v[82:97]
	v_add_u32_e32 v146, -8, v179
	global_load_dwordx2 v[146:147], v146, s[68:69]
	v_lshl_add_u64 v[194:195], v[188:189], 0, v[170:171]
	v_add_co_u32_e32 v130, vcc, s76, v194
	v_lshl_add_u64 v[192:193], v[190:191], 0, v[170:171]
	s_nop 0
	v_addc_co_u32_e32 v131, vcc, 0, v195, vcc
	v_add_co_u32_e32 v134, vcc, s77, v194
	s_nop 1
	v_addc_co_u32_e32 v135, vcc, 0, v195, vcc
	v_add_co_u32_e32 v138, vcc, s76, v192
	global_load_dwordx4 v[130:133], v[130:131], off
	s_nop 0
	global_load_dwordx4 v[134:137], v[134:135], off
	v_addc_co_u32_e32 v139, vcc, 0, v193, vcc
	v_add_co_u32_e32 v142, vcc, s77, v192
	s_nop 1
	v_addc_co_u32_e32 v143, vcc, 0, v193, vcc
	global_load_dwordx4 v[138:141], v[138:139], off
	s_nop 0
	global_load_dwordx4 v[142:145], v[142:143], off
	ds_read_b64_tr_b16 v[172:173], v1 offset:0
	ds_read_b64_tr_b16 v[174:175], v1 offset:0x800
	ds_read_b64_tr_b16 v[212:213], v1 offset:0x1000
	ds_read_b64_tr_b16 v[214:215], v1 offset:0x1800
	ds_read_b64_tr_b16 v[216:217], v1 offset:0x2000
	ds_read_b64_tr_b16 v[218:219], v1 offset:0x2800
	ds_read_b64_tr_b16 v[220:221], v1 offset:0x3000
	ds_read_b64_tr_b16 v[222:223], v1 offset:0x3800
	s_waitcnt lgkmcnt(0)
; __device__ __forceinline__ void sel_mask_tile(f32x16& p0, f32x16& p1, unsigned wlo, unsigned whi, int hi) {
;     const unsigned NEGB = 0xff800000u;
;     const unsigned lo = wlo >> (4 * hi), h2 = whi >> (4 * hi);
; #pragma unroll
;     for (int r = 0; r < 16; ++r) {
;         const int c = (r & 3) + 8 * (r >> 2);
;         const unsigned m0 = (unsigned)__builtin_amdgcn_sbfe((int)lo, c, 1), m1 = (unsigned)__builtin_amdgcn_sbfe((int)h2, c, 1);
;         p0[r] = __uint_as_float((__float_as_uint(p0[r]) & m0) | (NEGB & ~m0));
;         p1[r] = __uint_as_float((__float_as_uint(p1[r]) & m1) | (NEGB & ~m1));
;     }
; }
; __device__ __forceinline__ void partialSM(f32x16& p0, f32x16& p1, float& m_reg, float& mn, float& alpha) {
;     float pmax = p0[0];
; #pragma unroll
;     for (int r = 1; r < 16; ++r) pmax = fmaxf(pmax, p0[r]);
; #pragma unroll
;     for (int r = 0; r < 16; ++r) pmax = fmaxf(pmax, p1[r]);
;     { auto rr = __builtin_amdgcn_permlane32_swap(__float_as_uint(pmax), __float_as_uint(pmax), false, false);
;       pmax = fmaxf(__uint_as_float(rr[0]), __uint_as_float(rr[1])); }
;     constexpr float C2 = 1.4426950408889634f * SCALE;
;     if (__builtin_expect(__all((pmax - m_reg) * SCALE <= THR), 1)) { mn = m_reg; alpha = 1.f; }
;     else { mn = fmaxf(m_reg, pmax); alpha = __builtin_amdgcn_exp2f((m_reg - mn) * C2); m_reg = mn; }
; template <int VB>
; __device__ __forceinline__ void pv_tile(f32x16* o, int vb0, bf16x8 pa0, bf16x8 pa1, bf16x8 pa2, bf16x8 pa3) {
;     ...
;     PV_D0(0); PV_D0(1); PV_D0(2); PV_D0(3);
	s_nop 0
	v_mfma_f32_32x32x16_bf16 v[2:17], v[148:151], v[172:175], v[2:17]
	ds_read_b64_tr_b16 v[172:173], v1 offset:0x200
	ds_read_b64_tr_b16 v[174:175], v1 offset:0xa00
	v_mfma_f32_32x32x16_bf16 v[2:17], v[152:155], v[212:215], v[2:17]
	ds_read_b64_tr_b16 v[212:213], v1 offset:0x1200
	ds_read_b64_tr_b16 v[214:215], v1 offset:0x1a00
	v_mfma_f32_32x32x16_bf16 v[2:17], v[156:159], v[216:219], v[2:17]
	ds_read_b64_tr_b16 v[216:217], v1 offset:0x2200
	ds_read_b64_tr_b16 v[218:219], v1 offset:0x2a00
	ds_read_b64_tr_b16 v[224:225], v1 offset:0x3200
	ds_read_b64_tr_b16 v[226:227], v1 offset:0x3a00
	s_waitcnt lgkmcnt(0)
	v_mfma_f32_32x32x16_bf16 v[2:17], v[208:211], v[220:223], v[2:17]
	v_mfma_f32_32x32x16_bf16 v[50:65], v[148:151], v[172:175], v[50:65]
	ds_read_b64_tr_b16 v[172:173], v1 offset:0x400
	ds_read_b64_tr_b16 v[174:175], v1 offset:0xc00
	v_mfma_f32_32x32x16_bf16 v[50:65], v[152:155], v[212:215], v[50:65]
	ds_read_b64_tr_b16 v[212:213], v1 offset:0x1400
	ds_read_b64_tr_b16 v[214:215], v1 offset:0x1c00
	v_mfma_f32_32x32x16_bf16 v[50:65], v[156:159], v[216:219], v[50:65]
	ds_read_b64_tr_b16 v[216:217], v1 offset:0x2400
	ds_read_b64_tr_b16 v[218:219], v1 offset:0x2c00
	ds_read_b64_tr_b16 v[220:221], v1 offset:0x3400
	ds_read_b64_tr_b16 v[222:223], v1 offset:0x3c00
	s_waitcnt lgkmcnt(0)
	v_mfma_f32_32x32x16_bf16 v[50:65], v[208:211], v[224:227], v[50:65]
	v_mfma_f32_32x32x16_bf16 v[34:49], v[148:151], v[172:175], v[34:49]
	ds_read_b64_tr_b16 v[172:173], v1 offset:0x600
	ds_read_b64_tr_b16 v[174:175], v1 offset:0xe00
	v_mfma_f32_32x32x16_bf16 v[34:49], v[152:155], v[212:215], v[34:49]
	ds_read_b64_tr_b16 v[212:213], v1 offset:0x1600
	ds_read_b64_tr_b16 v[214:215], v1 offset:0x1e00
	v_mfma_f32_32x32x16_bf16 v[34:49], v[156:159], v[216:219], v[34:49]
	ds_read_b64_tr_b16 v[216:217], v1 offset:0x2600
	ds_read_b64_tr_b16 v[218:219], v1 offset:0x2e00
	ds_read_b64_tr_b16 v[224:225], v1 offset:0x3600
	ds_read_b64_tr_b16 v[226:227], v1 offset:0x3e00
	s_waitcnt lgkmcnt(0)
	v_mfma_f32_32x32x16_bf16 v[34:49], v[208:211], v[220:223], v[34:49]
	s_waitcnt vmcnt(4)
	v_lshrrev_b32_e32 v160, v163, v146
	v_lshrrev_b32_e32 v161, v163, v147
	v_bfe_i32 v146, v160, 0, 1
	v_bfe_i32 v147, v161, 0, 1
	v_bitop3_b32 v146, v66, s74, v146 bitop3:0xe4
	v_bitop3_b32 v66, v82, s74, v147 bitop3:0xe4
	v_bfe_i32 v82, v160, 1, 1
	v_bfe_i32 v147, v161, 1, 1
	v_bitop3_b32 v82, v67, s74, v82 bitop3:0xe4
	v_bitop3_b32 v67, v83, s74, v147 bitop3:0xe4
	v_bfe_i32 v83, v160, 2, 1
	v_bfe_i32 v147, v161, 2, 1
	v_bitop3_b32 v83, v68, s74, v83 bitop3:0xe4
	v_bitop3_b32 v68, v84, s74, v147 bitop3:0xe4
	v_bfe_i32 v84, v160, 3, 1
	v_mfma_f32_32x32x16_bf16 v[18:33], v[148:151], v[172:175], v[18:33]
	v_bfe_i32 v148, v161, 3, 1
	v_bitop3_b32 v147, v69, s74, v84 bitop3:0xe4
	v_bfe_i32 v84, v160, 8, 1
	v_bitop3_b32 v69, v85, s74, v148 bitop3:0xe4
	v_bfe_i32 v85, v161, 8, 1
	v_bitop3_b32 v148, v70, s74, v84 bitop3:0xe4
	v_bfe_i32 v84, v160, 9, 1
	v_bitop3_b32 v70, v86, s74, v85 bitop3:0xe4
	v_bfe_i32 v85, v161, 9, 1
	v_bitop3_b32 v149, v71, s74, v84 bitop3:0xe4
	v_bfe_i32 v84, v160, 10, 1
	v_bitop3_b32 v71, v87, s74, v85 bitop3:0xe4
	v_bfe_i32 v85, v161, 10, 1
	v_bitop3_b32 v87, v72, s74, v84 bitop3:0xe4
	v_bfe_i32 v84, v160, 11, 1
	v_bitop3_b32 v72, v88, s74, v85 bitop3:0xe4
	v_bfe_i32 v85, v161, 11, 1
	v_bitop3_b32 v88, v73, s74, v84 bitop3:0xe4
	v_bfe_i32 v73, v160, 16, 1
	v_bitop3_b32 v84, v89, s74, v85 bitop3:0xe4
	v_bfe_i32 v85, v161, 16, 1
	v_bitop3_b32 v89, v74, s74, v73 bitop3:0xe4
	v_bfe_i32 v73, v160, 17, 1
	v_bfe_i32 v74, v161, 17, 1
	v_bitop3_b32 v85, v90, s74, v85 bitop3:0xe4
	v_bitop3_b32 v90, v75, s74, v73 bitop3:0xe4
	v_bitop3_b32 v86, v91, s74, v74 bitop3:0xe4
	v_bfe_i32 v73, v160, 18, 1
	v_bfe_i32 v74, v161, 18, 1
	v_bitop3_b32 v91, v76, s74, v73 bitop3:0xe4
	v_bitop3_b32 v76, v92, s74, v74 bitop3:0xe4
	v_bfe_i32 v73, v160, 19, 1
	v_bfe_i32 v74, v161, 19, 1
	v_bitop3_b32 v92, v77, s74, v73 bitop3:0xe4
	v_bitop3_b32 v77, v93, s74, v74 bitop3:0xe4
	v_bfe_i32 v73, v160, 24, 1
	v_bfe_i32 v74, v161, 24, 1
	v_bitop3_b32 v93, v78, s74, v73 bitop3:0xe4
	v_bitop3_b32 v78, v94, s74, v74 bitop3:0xe4
	v_bfe_i32 v73, v160, 25, 1
	v_bfe_i32 v74, v161, 25, 1
	v_bitop3_b32 v79, v79, s74, v73 bitop3:0xe4
	v_bitop3_b32 v73, v95, s74, v74 bitop3:0xe4
	v_bfe_i32 v74, v160, 26, 1
	v_bfe_i32 v75, v161, 26, 1
	v_bitop3_b32 v80, v80, s74, v74 bitop3:0xe4
	v_bitop3_b32 v74, v96, s74, v75 bitop3:0xe4
	v_bfe_i32 v75, v160, 27, 1
	v_bfe_i32 v94, v161, 27, 1
	v_bitop3_b32 v81, v81, s74, v75 bitop3:0xe4
	v_bitop3_b32 v75, v97, s74, v94 bitop3:0xe4
	v_max_f32_e32 v94, v82, v82
	v_max_f32_e32 v95, v146, v146
	v_max_f32_e32 v94, v95, v94
	v_max3_f32 v94, v94, v83, v147
	v_max3_f32 v94, v94, v148, v149
	v_max3_f32 v94, v94, v87, v88
	v_max3_f32 v94, v94, v89, v90
	v_mfma_f32_32x32x16_bf16 v[18:33], v[152:155], v[212:215], v[18:33]
	v_max3_f32 v94, v94, v91, v92
	v_max3_f32 v94, v94, v93, v79
	v_max3_f32 v94, v94, v80, v81
	v_max3_f32 v94, v94, v66, v67
	v_max3_f32 v94, v94, v68, v69
	v_max3_f32 v94, v94, v70, v71
	v_max3_f32 v94, v94, v72, v84
	v_max3_f32 v94, v94, v85, v86
	v_mfma_f32_32x32x16_bf16 v[18:33], v[156:159], v[216:219], v[18:33]
	v_max3_f32 v94, v94, v76, v77
	v_max3_f32 v94, v94, v78, v73
	v_max3_f32 v94, v94, v74, v75
	v_mov_b32_e32 v95, v94
	s_nop 1
	v_permlane32_swap_b32_e32 v94, v95
	v_max_f32_e32 v95, v95, v95
	v_max_f32_e32 v94, v94, v94
	v_max_f32_e32 v94, v94, v95
	v_max_f32_e32 v96, v206, v206
	v_sub_f32_e32 v95, v94, v206
	v_max_f32_e32 v94, v96, v94
	v_mfma_f32_32x32x16_bf16 v[18:33], v[208:211], v[224:227], v[18:33]
	v_sub_f32_e32 v96, v206, v94
	v_mul_f32_e32 v96, 0x3e0293ee, v96
	v_mul_f32_e32 v95, 0x3db504f3, v95
	v_exp_f32_e32 v96, v96
	v_cmp_ge_f32_e32 vcc, s75, v95
	s_cmp_eq_u64 vcc, exec
	s_cselect_b64 s[6:7], -1, 0
	s_barrier
; __device__ __forceinline__ void partialSM(f32x16& p0, f32x16& p1, float& m_reg, float& mn, float& alpha) {
;     ...
;     const float mnL = -mn * C2;
; #pragma unroll
;     for (int r = 0; r < 16; ++r) p0[r] = fmaf(p0[r], C2, mnL);
; #pragma unroll
;     for (int r = 0; r < 16; ++r) p1[r] = fmaf(p1[r], C2, mnL);
; #pragma unroll
;     for (int r = 0; r < 16; ++r) p0[r] = __builtin_amdgcn_exp2f(p0[r]);
	s_waitcnt vmcnt(0)
	v_cndmask_b32_e64 v208, v96, 1.0, s[6:7]
	v_cmp_gt_f32_e32 vcc, 1.0, v208
	ds_write_b128 v197, v[130:133]
	ds_write_b128 v198, v[134:137]
	ds_write_b128 v204, v[138:141] offset:32768
	ds_write_b128 v204, v[142:145] offset:40960
	s_cbranch_vccz .LBB0_1303
	s_and_saveexec_b64 s[36:37], s[0:1]
	ds_write_b32 v185, v208 offset:128
	s_or_b64 exec, exec, s[36:37]
	s_waitcnt lgkmcnt(0)
	ds_read_b128 v[150:153], v183 offset:224
	ds_read_b128 v[154:157], v183 offset:192
	ds_read_b128 v[158:161], v183 offset:160
	ds_read_b128 v[172:175], v183 offset:128
	s_waitcnt lgkmcnt(3)
	v_pk_mul_f32 v[16:17], v[16:17], v[152:153]
	s_waitcnt lgkmcnt(2)
	v_pk_mul_f32 v[12:13], v[12:13], v[156:157]
	s_waitcnt lgkmcnt(1)
	v_pk_mul_f32 v[8:9], v[8:9], v[160:161]
	s_waitcnt lgkmcnt(0)
	v_pk_mul_f32 v[4:5], v[4:5], v[174:175]
	v_pk_mul_f32 v[14:15], v[14:15], v[150:151]
	v_pk_mul_f32 v[10:11], v[10:11], v[154:155]
	v_pk_mul_f32 v[6:7], v[6:7], v[158:159]
	v_pk_mul_f32 v[2:3], v[2:3], v[172:173]
	v_pk_mul_f32 v[64:65], v[64:65], v[152:153]
	v_pk_mul_f32 v[60:61], v[60:61], v[156:157]
	v_pk_mul_f32 v[56:57], v[56:57], v[160:161]
	v_pk_mul_f32 v[52:53], v[52:53], v[174:175]
	v_pk_mul_f32 v[62:63], v[62:63], v[150:151]
	v_pk_mul_f32 v[58:59], v[58:59], v[154:155]
	v_pk_mul_f32 v[54:55], v[54:55], v[158:159]
	v_pk_mul_f32 v[50:51], v[50:51], v[172:173]
	v_pk_mul_f32 v[48:49], v[48:49], v[152:153]
	v_pk_mul_f32 v[44:45], v[44:45], v[156:157]
	v_pk_mul_f32 v[40:41], v[40:41], v[160:161]
	v_pk_mul_f32 v[36:37], v[36:37], v[174:175]
	v_pk_mul_f32 v[46:47], v[46:47], v[150:151]
	v_pk_mul_f32 v[42:43], v[42:43], v[154:155]
	v_pk_mul_f32 v[38:39], v[38:39], v[158:159]
	v_pk_mul_f32 v[34:35], v[34:35], v[172:173]
	v_pk_mul_f32 v[32:33], v[32:33], v[152:153]
	v_pk_mul_f32 v[28:29], v[28:29], v[156:157]
	v_pk_mul_f32 v[24:25], v[24:25], v[160:161]
	v_pk_mul_f32 v[20:21], v[20:21], v[174:175]
	v_pk_mul_f32 v[30:31], v[30:31], v[150:151]
	v_pk_mul_f32 v[26:27], v[26:27], v[154:155]
	v_pk_mul_f32 v[22:23], v[22:23], v[158:159]
	v_pk_mul_f32 v[18:19], v[18:19], v[172:173]
.LBB0_1303:
	v_cndmask_b32_e64 v206, v94, v206, s[6:7]
	v_mul_f32_e32 v207, 0xbe0293ee, v206
	v_fmamk_f32 v94, v146, 0x3e0293ee, v207
	v_fmamk_f32 v82, v82, 0x3e0293ee, v207
	v_fmamk_f32 v83, v83, 0x3e0293ee, v207
	v_fmamk_f32 v95, v147, 0x3e0293ee, v207
	v_fmamk_f32 v96, v148, 0x3e0293ee, v207
	v_fmamk_f32 v97, v149, 0x3e0293ee, v207
	v_fmamk_f32 v87, v87, 0x3e0293ee, v207
	v_fmamk_f32 v88, v88, 0x3e0293ee, v207
	v_fmamk_f32 v89, v89, 0x3e0293ee, v207
	v_fmamk_f32 v90, v90, 0x3e0293ee, v207
	v_fmamk_f32 v91, v91, 0x3e0293ee, v207
	v_fmamk_f32 v92, v92, 0x3e0293ee, v207
	v_fmamk_f32 v93, v93, 0x3e0293ee, v207
	v_fmamk_f32 v79, v79, 0x3e0293ee, v207
	v_fmamk_f32 v80, v80, 0x3e0293ee, v207
	v_fmamk_f32 v81, v81, 0x3e0293ee, v207
	v_exp_f32_e32 v146, v94
	v_exp_f32_e32 v147, v82
	v_exp_f32_e32 v148, v83
	v_exp_f32_e32 v159, v95
	v_exp_f32_e32 v160, v96
	v_exp_f32_e32 v161, v97
	v_exp_f32_e32 v149, v87
	v_exp_f32_e32 v158, v88
	v_exp_f32_e32 v150, v89
	v_exp_f32_e32 v151, v90
	v_exp_f32_e32 v155, v91
	v_exp_f32_e32 v157, v92
	v_exp_f32_e32 v152, v93
	v_exp_f32_e32 v153, v79
	v_exp_f32_e32 v154, v80
	v_exp_f32_e32 v156, v81
	v_fmamk_f32 v210, v71, 0x3e0293ee, v207
	v_fmamk_f32 v209, v78, 0x3e0293ee, v207
	v_fmamk_f32 v217, v66, 0x3e0293ee, v207
	v_fmamk_f32 v218, v67, 0x3e0293ee, v207
	v_fmamk_f32 v219, v68, 0x3e0293ee, v207
	v_fmamk_f32 v220, v69, 0x3e0293ee, v207
	v_fmamk_f32 v221, v70, 0x3e0293ee, v207
	v_fmamk_f32 v211, v72, 0x3e0293ee, v207
	v_fmamk_f32 v212, v84, 0x3e0293ee, v207
	v_fmamk_f32 v213, v85, 0x3e0293ee, v207
	v_fmamk_f32 v214, v86, 0x3e0293ee, v207
	v_fmamk_f32 v215, v76, 0x3e0293ee, v207
	v_fmamk_f32 v216, v77, 0x3e0293ee, v207
	v_fmamk_f32 v222, v73, 0x3e0293ee, v207
	v_fmamk_f32 v223, v74, 0x3e0293ee, v207
	v_fmac_f32_e32 v207, 0x3e0293ee, v75
	s_waitcnt lgkmcnt(0)
	s_barrier
	global_load_dwordx2 v[228:229], v179, s[68:69]
	ds_read_b128 v[66:69], v199 offset:32768
	ds_read_b128 v[70:73], v199 offset:40960
	ds_read_b128 v[172:175], v200 offset:32768
	ds_read_b128 v[224:227], v200 offset:40960
	ds_read_b128 v[130:133], v201 offset:32768
	ds_read_b128 v[134:137], v201 offset:40960
	ds_read_b128 v[138:141], v202 offset:32768
	ds_read_b128 v[142:145], v202 offset:40960
	ds_read_b128 v[232:235], v199 offset:32896
	ds_read_b128 v[236:239], v199 offset:41088
	ds_read_b128 v[240:243], v200 offset:32896
	ds_read_b128 v[244:247], v200 offset:41088
	v_exp_f32_e32 v211, v211
	v_exp_f32_e32 v212, v212
	s_waitcnt lgkmcnt(11)
	v_mfma_f32_32x32x16_bf16 v[82:97], v[66:69], v[126:129], 0
	v_exp_f32_e32 v213, v213
	v_exp_f32_e32 v214, v214
	v_exp_f32_e32 v215, v215
	s_waitcnt lgkmcnt(10)
	v_mfma_f32_32x32x16_bf16 v[66:81], v[70:73], v[126:129], 0
	v_exp_f32_e32 v216, v216
	v_exp_f32_e32 v207, v207
	s_waitcnt lgkmcnt(9)
	v_mfma_f32_32x32x16_bf16 v[82:97], v[172:175], v[122:125], v[82:97]
	ds_read_b128 v[172:175], v201 offset:32896
	v_exp_f32_e32 v250, v219
	v_exp_f32_e32 v219, v209
	v_add_f32_e32 v209, 0, v146
	v_add_f32_e32 v209, v147, v209
	s_waitcnt lgkmcnt(9)
	v_mfma_f32_32x32x16_bf16 v[66:81], v[224:227], v[122:125], v[66:81]
	ds_read_b128 v[224:227], v201 offset:41088
	v_add_f32_e32 v209, v148, v209
	v_add_f32_e32 v209, v159, v209
	v_add_f32_e32 v209, v160, v209
	v_add_f32_e32 v209, v161, v209
	v_add_f32_e32 v209, v149, v209
	s_waitcnt lgkmcnt(9)
	v_mfma_f32_32x32x16_bf16 v[82:97], v[130:133], v[118:121], v[82:97]
	ds_read_b128 v[130:133], v202 offset:32896
	v_add_f32_e32 v209, v158, v209
	v_add_f32_e32 v209, v150, v209
	v_add_f32_e32 v209, v151, v209
	v_add_f32_e32 v209, v155, v209
	v_add_f32_e32 v209, v157, v209
	s_waitcnt lgkmcnt(9)
; __device__ __forceinline__ void finishSM(f32x16& p0, f32x16& p1, float alpha, float& l_reg, bf16x8& pa0, bf16x8& pa1, bf16x8& pa2, bf16x8& pa3) {
; #pragma unroll
;     for (int r = 0; r < 16; ++r) p1[r] = __builtin_amdgcn_exp2f(p1[r]);
;     float ps = 0;
; #pragma unroll
;     for (int r = 0; r < 16; ++r) ps += p0[r];
; #pragma unroll
;     for (int r = 0; r < 16; ++r) ps += p1[r];
;     { auto rr = __builtin_amdgcn_permlane32_swap(__float_as_uint(ps), __float_as_uint(ps), false, false);
;       ps = __uint_as_float(rr[0]) + __uint_as_float(rr[1]); }
;     l_reg = l_reg * alpha + ps;
;     ...
;     PK4(p0, 0, pa0); PK4(p0, 8, pa1); PK4(p1, 0, pa2); PK4(p1, 8, pa3);
;     ...
; }
; template <int KB>
; __device__ __forceinline__ void qkt(f32x16& p0, f32x16& p1, const char* K_lds, int r32, int hi, const bf16x8* qr) {
;     p0 = f32x16{}; p1 = f32x16{};
;     const char* kb[4];
; #pragma unroll
;     for (int dd = 0; dd < 4; ++dd) kb[dd] = K_lds + KB * SHM_K + KSWZ(r32, (dd * 16 + hi * 8) * 2);
; #pragma unroll
;     for (int d0 = 0; d0 < 8; ++d0) { const char* a = kb[d0 & 3] + (d0 >> 2) * 128;
;         bf16x8 b0 = *reinterpret_cast<const bf16x8*>(a);
;         bf16x8 b1 = *reinterpret_cast<const bf16x8*>(a + 32 * 256);
;         p0 = __builtin_amdgcn_mfma_f32_32x32x16_bf16(b0, qr[d0], p0, 0, 0, 0);
;         p1 = __builtin_amdgcn_mfma_f32_32x32x16_bf16(b1, qr[d0], p1, 0, 0, 0); }
; }
	v_mfma_f32_32x32x16_bf16 v[66:81], v[134:137], v[118:121], v[66:81]
	ds_read_b128 v[134:137], v202 offset:41088
	v_exp_f32_e32 v248, v217
	v_add_f32_e32 v209, v152, v209
	v_exp_f32_e32 v249, v218
	s_waitcnt lgkmcnt(9)
	v_mfma_f32_32x32x16_bf16 v[82:97], v[138:141], v[114:117], v[82:97]
	v_add_f32_e32 v209, v153, v209
	v_add_f32_e32 v209, v154, v209
	v_exp_f32_e32 v251, v220
	v_add_f32_e32 v209, v156, v209
	s_waitcnt lgkmcnt(8)
	v_mfma_f32_32x32x16_bf16 v[66:81], v[142:145], v[114:117], v[66:81]
	v_exp_f32_e32 v217, v221
	v_add_f32_e32 v209, v248, v209
	v_exp_f32_e32 v218, v210
	s_waitcnt lgkmcnt(7)
	v_mfma_f32_32x32x16_bf16 v[82:97], v[232:235], v[110:113], v[82:97]
	v_add_f32_e32 v209, v249, v209
	v_add_f32_e32 v209, v250, v209
	v_add_f32_e32 v209, v251, v209
	v_add_f32_e32 v209, v217, v209
	v_add_f32_e32 v209, v218, v209
	s_waitcnt lgkmcnt(6)
	v_mfma_f32_32x32x16_bf16 v[66:81], v[236:239], v[110:113], v[66:81]
	v_add_f32_e32 v209, v211, v209
	v_add_f32_e32 v209, v212, v209
	v_add_f32_e32 v209, v213, v209
	v_exp_f32_e32 v220, v222
	s_waitcnt lgkmcnt(5)
	v_mfma_f32_32x32x16_bf16 v[82:97], v[240:243], v[106:109], v[82:97]
	v_add_f32_e32 v209, v214, v209
	v_exp_f32_e32 v221, v223
	v_add_f32_e32 v209, v215, v209
	v_add_f32_e32 v209, v216, v209
	s_waitcnt lgkmcnt(4)
	v_mfma_f32_32x32x16_bf16 v[66:81], v[244:247], v[106:109], v[66:81]
	v_add_f32_e32 v209, v219, v209
	v_add_f32_e32 v209, v220, v209
	v_add_f32_e32 v209, v221, v209
	v_add_f32_e32 v209, v207, v209
	v_mov_b32_e32 v210, v209
	s_waitcnt lgkmcnt(3)
	v_mfma_f32_32x32x16_bf16 v[82:97], v[172:175], v[102:105], v[82:97]
	v_cvt_pk_bf16_f32 v146, v146, v147
	v_cvt_pk_bf16_f32 v147, v148, v159
	v_cvt_pk_bf16_f32 v148, v160, v161
	v_cvt_pk_bf16_f32 v149, v149, v158
	v_cvt_pk_bf16_f32 v150, v150, v151
	s_waitcnt lgkmcnt(2)
	v_mfma_f32_32x32x16_bf16 v[66:81], v[224:227], v[102:105], v[66:81]
	v_cvt_pk_bf16_f32 v151, v155, v157
	v_cvt_pk_bf16_f32 v152, v152, v153
	v_cvt_pk_bf16_f32 v153, v154, v156
	v_cvt_pk_bf16_f32 v154, v248, v249
	v_cvt_pk_bf16_f32 v155, v250, v251
	s_waitcnt lgkmcnt(1)
	v_mfma_f32_32x32x16_bf16 v[82:97], v[130:133], v[98:101], v[82:97]
	v_cvt_pk_bf16_f32 v156, v217, v218
	v_cvt_pk_bf16_f32 v157, v211, v212
	v_cvt_pk_bf16_f32 v158, v213, v214
	v_cvt_pk_bf16_f32 v159, v215, v216
	v_cvt_pk_bf16_f32 v160, v219, v220
	s_waitcnt lgkmcnt(0)
	v_mfma_f32_32x32x16_bf16 v[66:81], v[134:137], v[98:101], v[66:81]
	v_cvt_pk_bf16_f32 v161, v221, v207
	v_permlane32_swap_b32_e32 v209, v210
	v_permlane32_swap_b32_e32 v146, v148
	v_permlane32_swap_b32_e32 v147, v149
	v_permlane32_swap_b32_e32 v150, v152
	v_permlane32_swap_b32_e32 v151, v153
	v_permlane32_swap_b32_e32 v154, v156
	v_permlane32_swap_b32_e32 v155, v157
	v_permlane32_swap_b32_e32 v158, v160
	v_permlane32_swap_b32_e32 v159, v161
	s_add_i32 s82, s82, 2
	s_cmp_le_u32 s82, s81
	s_cselect_b64 s[36:37], -1, 0
	s_cmp_gt_u32 s82, s81
	s_cbranch_scc1 .Lp5_skip_ld
	v_add_co_u32_e32 v130, vcc, 0x60000, v194
	s_nop 1
	v_addc_co_u32_e32 v131, vcc, 0, v195, vcc
	v_add_co_u32_e32 v134, vcc, 0x70000, v194
	s_nop 1
	v_addc_co_u32_e32 v135, vcc, 0, v195, vcc
	v_add_co_u32_e32 v138, vcc, 0x60000, v192
	global_load_dwordx4 v[130:133], v[130:131], off
	s_nop 0
	global_load_dwordx4 v[134:137], v[134:135], off
	v_addc_co_u32_e32 v139, vcc, 0, v193, vcc
	v_add_co_u32_e32 v142, vcc, 0x70000, v192
	s_nop 1
	v_addc_co_u32_e32 v143, vcc, 0, v193, vcc
	global_load_dwordx4 v[138:141], v[138:139], off
	s_nop 0
	global_load_dwordx4 v[142:145], v[142:143], off
; __device__ __forceinline__ void sel_mask_tile(f32x16& p0, f32x16& p1, unsigned wlo, unsigned whi, int hi) {
;     const unsigned NEGB = 0xff800000u;
;     const unsigned lo = wlo >> (4 * hi), h2 = whi >> (4 * hi);
; #pragma unroll
;     for (int r = 0; r < 16; ++r) {
;         const int c = (r & 3) + 8 * (r >> 2);
;         const unsigned m0 = (unsigned)__builtin_amdgcn_sbfe((int)lo, c, 1), m1 = (unsigned)__builtin_amdgcn_sbfe((int)h2, c, 1);
;         p0[r] = __uint_as_float((__float_as_uint(p0[r]) & m0) | (NEGB & ~m0));
;         p1[r] = __uint_as_float((__float_as_uint(p1[r]) & m1) | (NEGB & ~m1));
;     }
; }
; __device__ __forceinline__ void partialSM(f32x16& p0, f32x16& p1, float& m_reg, float& mn, float& alpha) {
;     float pmax = p0[0];
; #pragma unroll
;     for (int r = 1; r < 16; ++r) pmax = fmaxf(pmax, p0[r]);
; #pragma unroll
;     for (int r = 0; r < 16; ++r) pmax = fmaxf(pmax, p1[r]);
;     { auto rr = __builtin_amdgcn_permlane32_swap(__float_as_uint(pmax), __float_as_uint(pmax), false, false);
;       pmax = fmaxf(__uint_as_float(rr[0]), __uint_as_float(rr[1])); }
;     constexpr float C2 = 1.4426950408889634f * SCALE;
;     if (__builtin_expect(__all((pmax - m_reg) * SCALE <= THR), 1)) { mn = m_reg; alpha = 1.f; }
;     else { mn = fmaxf(m_reg, pmax); alpha = __builtin_amdgcn_exp2f((m_reg - mn) * C2); m_reg = mn; }
; template <int VB>
; __device__ __forceinline__ void pv_tile(f32x16* o, int vb0, bf16x8 pa0, bf16x8 pa1, bf16x8 pa2, bf16x8 pa3) {
;     ...
;     PV_D0(0); PV_D0(1); PV_D0(2); PV_D0(3);
.LBB0_1305:
	ds_read_b64_tr_b16 v[172:173], v1 offset:0x4000
	ds_read_b64_tr_b16 v[174:175], v1 offset:0x4800
	ds_read_b64_tr_b16 v[192:193], v1 offset:0x5000
	ds_read_b64_tr_b16 v[194:195], v1 offset:0x5800
	ds_read_b64_tr_b16 v[212:213], v1 offset:0x6000
	ds_read_b64_tr_b16 v[214:215], v1 offset:0x6800
	ds_read_b64_tr_b16 v[216:217], v1 offset:0x7000
	ds_read_b64_tr_b16 v[218:219], v1 offset:0x7800
	s_waitcnt lgkmcnt(0)
	s_nop 0
	v_mfma_f32_32x32x16_bf16 v[2:17], v[146:149], v[172:175], v[2:17]
	ds_read_b64_tr_b16 v[172:173], v1 offset:0x4200
	ds_read_b64_tr_b16 v[174:175], v1 offset:0x4a00
	v_mfma_f32_32x32x16_bf16 v[2:17], v[150:153], v[192:195], v[2:17]
	ds_read_b64_tr_b16 v[192:193], v1 offset:0x5200
	ds_read_b64_tr_b16 v[194:195], v1 offset:0x5a00
	v_mfma_f32_32x32x16_bf16 v[2:17], v[154:157], v[212:215], v[2:17]
	ds_read_b64_tr_b16 v[212:213], v1 offset:0x6200
	ds_read_b64_tr_b16 v[214:215], v1 offset:0x6a00
	ds_read_b64_tr_b16 v[220:221], v1 offset:0x7200
	ds_read_b64_tr_b16 v[222:223], v1 offset:0x7a00
	s_waitcnt lgkmcnt(0)
	v_mfma_f32_32x32x16_bf16 v[2:17], v[158:161], v[216:219], v[2:17]
	v_mfma_f32_32x32x16_bf16 v[50:65], v[146:149], v[172:175], v[50:65]
	ds_read_b64_tr_b16 v[172:173], v1 offset:0x4400
	ds_read_b64_tr_b16 v[174:175], v1 offset:0x4c00
	v_mfma_f32_32x32x16_bf16 v[50:65], v[150:153], v[192:195], v[50:65]
	ds_read_b64_tr_b16 v[192:193], v1 offset:0x5400
	ds_read_b64_tr_b16 v[194:195], v1 offset:0x5c00
	v_mfma_f32_32x32x16_bf16 v[50:65], v[154:157], v[212:215], v[50:65]
	ds_read_b64_tr_b16 v[212:213], v1 offset:0x6400
	ds_read_b64_tr_b16 v[214:215], v1 offset:0x6c00
	ds_read_b64_tr_b16 v[216:217], v1 offset:0x7400
	ds_read_b64_tr_b16 v[218:219], v1 offset:0x7c00
	s_waitcnt lgkmcnt(0)
	v_mfma_f32_32x32x16_bf16 v[50:65], v[158:161], v[220:223], v[50:65]
	v_mfma_f32_32x32x16_bf16 v[34:49], v[146:149], v[172:175], v[34:49]
	ds_read_b64_tr_b16 v[172:173], v1 offset:0x4600
	ds_read_b64_tr_b16 v[174:175], v1 offset:0x4e00
	v_mfma_f32_32x32x16_bf16 v[34:49], v[150:153], v[192:195], v[34:49]
	v_mfma_f32_32x32x16_bf16 v[34:49], v[154:157], v[212:215], v[34:49]
	ds_read_b64_tr_b16 v[212:213], v1 offset:0x5600
	ds_read_b64_tr_b16 v[214:215], v1 offset:0x5e00
	ds_read_b64_tr_b16 v[220:221], v1 offset:0x6600
	ds_read_b64_tr_b16 v[222:223], v1 offset:0x6e00
	ds_read_b64_tr_b16 v[224:225], v1 offset:0x7600
	ds_read_b64_tr_b16 v[226:227], v1 offset:0x7e00
	s_waitcnt lgkmcnt(0)
	v_mfma_f32_32x32x16_bf16 v[34:49], v[158:161], v[216:219], v[34:49]
	v_mfma_f32_32x32x16_bf16 v[18:33], v[146:149], v[172:175], v[18:33]
	s_waitcnt vmcnt(4)
	v_lshrrev_b32_e32 v193, v163, v228
	v_bfe_i32 v192, v193, 0, 1
	v_bitop3_b32 v192, v82, s74, v192 bitop3:0xe4
	v_bfe_i32 v82, v193, 1, 1
	v_bitop3_b32 v146, v83, s74, v82 bitop3:0xe4
	v_bfe_i32 v82, v193, 2, 1
	v_bitop3_b32 v147, v84, s74, v82 bitop3:0xe4
	v_mfma_f32_32x32x16_bf16 v[18:33], v[150:153], v[212:215], v[18:33]
	v_bfe_i32 v82, v193, 3, 1
	v_bitop3_b32 v148, v85, s74, v82 bitop3:0xe4
	v_bfe_i32 v82, v193, 8, 1
	v_bitop3_b32 v149, v86, s74, v82 bitop3:0xe4
	v_bfe_i32 v82, v193, 9, 1
	v_bitop3_b32 v150, v87, s74, v82 bitop3:0xe4
	v_bfe_i32 v82, v193, 10, 1
	v_bitop3_b32 v88, v88, s74, v82 bitop3:0xe4
	v_bfe_i32 v82, v193, 11, 1
	v_mfma_f32_32x32x16_bf16 v[18:33], v[154:157], v[220:223], v[18:33]
	v_bitop3_b32 v89, v89, s74, v82 bitop3:0xe4
	v_bfe_i32 v82, v193, 16, 1
	v_bitop3_b32 v90, v90, s74, v82 bitop3:0xe4
	v_bfe_i32 v82, v193, 17, 1
	v_bitop3_b32 v91, v91, s74, v82 bitop3:0xe4
	v_bfe_i32 v82, v193, 18, 1
	v_bitop3_b32 v92, v92, s74, v82 bitop3:0xe4
	v_bfe_i32 v82, v193, 19, 1
	v_bitop3_b32 v93, v93, s74, v82 bitop3:0xe4
	v_bfe_i32 v82, v193, 24, 1
	v_bitop3_b32 v94, v94, s74, v82 bitop3:0xe4
	v_bfe_i32 v82, v193, 25, 1
	v_bitop3_b32 v95, v95, s74, v82 bitop3:0xe4
	v_bfe_i32 v82, v193, 26, 1
	v_bitop3_b32 v96, v96, s74, v82 bitop3:0xe4
	v_bfe_i32 v82, v193, 27, 1
	v_mfma_f32_32x32x16_bf16 v[18:33], v[158:161], v[224:227], v[18:33]
	v_bitop3_b32 v97, v97, s74, v82 bitop3:0xe4
	v_max_f32_e32 v82, v146, v146
	v_max_f32_e32 v160, v192, v192
	v_max_f32_e32 v82, v160, v82
	v_max3_f32 v82, v82, v147, v148
	v_max3_f32 v82, v82, v149, v150
	v_max3_f32 v82, v82, v88, v89
	v_max3_f32 v82, v82, v90, v91
	v_lshrrev_b32_e32 v194, v163, v229
	v_max3_f32 v82, v82, v92, v93
	v_bfe_i32 v195, v194, 0, 1
	v_bfe_i32 v172, v194, 1, 1
	v_max3_f32 v82, v82, v94, v95
	v_bitop3_b32 v66, v66, s74, v195 bitop3:0xe4
	v_bfe_i32 v83, v194, 2, 1
	v_bfe_i32 v84, v194, 3, 1
	v_max3_f32 v160, v82, v96, v97
	v_bitop3_b32 v67, v67, s74, v172 bitop3:0xe4
	v_bfe_i32 v85, v194, 8, 1
	v_bfe_i32 v86, v194, 9, 1
	v_bitop3_b32 v82, v68, s74, v83 bitop3:0xe4
	v_max3_f32 v68, v160, v66, v67
	v_bitop3_b32 v83, v69, s74, v84 bitop3:0xe4
	v_bfe_i32 v87, v194, 10, 1
	v_bfe_i32 v151, v194, 11, 1
	v_bitop3_b32 v84, v70, s74, v85 bitop3:0xe4
	v_max3_f32 v68, v68, v82, v83
	v_bitop3_b32 v85, v71, s74, v86 bitop3:0xe4
	v_bfe_i32 v152, v194, 16, 1
	v_bfe_i32 v153, v194, 17, 1
	v_bitop3_b32 v86, v72, s74, v87 bitop3:0xe4
	v_max3_f32 v68, v68, v84, v85
	v_bitop3_b32 v87, v73, s74, v151 bitop3:0xe4
	v_bfe_i32 v154, v194, 18, 1
	v_bfe_i32 v155, v194, 19, 1
	v_bitop3_b32 v74, v74, s74, v152 bitop3:0xe4
	v_max3_f32 v69, v68, v86, v87
	v_bitop3_b32 v75, v75, s74, v153 bitop3:0xe4
	v_bfe_i32 v156, v194, 24, 1
	v_bfe_i32 v157, v194, 25, 1
	v_bitop3_b32 v68, v76, s74, v154 bitop3:0xe4
	v_max3_f32 v71, v69, v74, v75
	v_bitop3_b32 v69, v77, s74, v155 bitop3:0xe4
	v_bfe_i32 v158, v194, 26, 1
	v_bfe_i32 v159, v194, 27, 1
	v_bitop3_b32 v70, v78, s74, v156 bitop3:0xe4
	v_max3_f32 v73, v71, v68, v69
	v_bitop3_b32 v71, v79, s74, v157 bitop3:0xe4
	v_bitop3_b32 v72, v80, s74, v158 bitop3:0xe4
	v_max3_f32 v76, v73, v70, v71
	v_bitop3_b32 v73, v81, s74, v159 bitop3:0xe4
	v_max3_f32 v76, v76, v72, v73
	v_mov_b32_e32 v77, v76
	s_nop 1
	v_permlane32_swap_b32_e32 v76, v77
	v_max_f32_e32 v77, v77, v77
	v_max_f32_e32 v76, v76, v76
	v_max_f32_e32 v76, v76, v77
	v_sub_f32_e32 v77, v76, v206
	v_mul_f32_e32 v77, 0x3db504f3, v77
	v_cmp_ge_f32_e32 vcc, s75, v77
	s_cmp_eq_u64 vcc, exec
	s_cselect_b64 s[6:7], -1, 0
	s_andn2_b64 vcc, exec, s[36:37]
	s_barrier
	s_cbranch_vccnz .LBB0_1307
	s_waitcnt vmcnt(0)
	ds_write_b128 v197, v[130:133] offset:16384
	ds_write_b128 v198, v[134:137] offset:16384
	ds_write_b128 v204, v[138:141] offset:49152
	ds_write_b128 v204, v[142:145] offset:57344

.Lp5_skip_ld:
	s_waitcnt vmcnt(0)
	s_branch .LBB0_1305
